# attention phase rewritten by hand on v_mfma_f32_16x16x32_bf16 (K row permutation so P stays in registers, lazy rescale, cross-lane max/sum only in rescale path and epilogue)
# baseline (speedup 1.0000x reference)
.LBB0_1471:
	s_cmpk_gt_i32 s74, 0x5ff
	s_cbranch_scc1 .Latt16_done
	s_load_dword s41, s[78:79], 0xc8
	v_lshrrev_b32_e32 v132, 6, v144
	v_and_b32_e32 v133, 63, v144
	v_readfirstlane_b32 s11, v132
	v_and_b32_e32 v134, 15, v133
	v_lshrrev_b32_e32 v135, 4, v133
	v_lshrrev_b32_e32 v136, 3, v133
	v_and_b32_e32 v137, 7, v133
	v_xor_b32_e32 v138, v137, v136
	v_lshlrev_b32_e32 v138, 4, v138
	s_lshr_b32 s12, s11, 1
	s_lshl_b32 s12, s12, 5
	s_and_b32 s13, s11, 1
	s_lshl_b32 s13, s13, 2
	s_add_u32 s12, s12, s13
	v_lshrrev_b32_e32 v139, 2, v136
	v_and_b32_e32 v140, 3, v136
	v_lshl_add_u32 v139, v139, 3, v140
	v_add_u32_e32 v139, s12, v139
	v_mul_u32_u24_e32 v216, 0x600, v139
	v_add_u32_e32 v216, v216, v138
	v_add_u32_e32 v217, 0x6000, v216
	s_lshl_b32 s13, s11, 5
	v_add_u32_e32 v139, s13, v136
	v_mul_u32_u24_e32 v218, 0x4200, v139
	v_add_u32_e32 v218, v218, v138
	v_add_u32_e32 v219, 0x21000, v218
	v_add_u32_e32 v220, 0x42000, v218
	v_add_u32_e32 v221, 0x63000, v218
	v_and_b32_e32 v139, 7, v134
	v_xor_b32_e32 v139, v139, v135
	v_lshlrev_b32_e32 v222, 7, v134
	v_lshl_add_u32 v222, v139, 4, v222
	v_xor_b32_e32 v223, 64, v222
	v_mul_u32_u24_e32 v224, 0x600, v134
	v_lshl_add_u32 v224, v135, 4, v224
	v_add_u32_e32 v225, 0x6000, v224
	v_xor_b32_e32 v226, 16, v133
	v_lshlrev_b32_e32 v226, 2, v226
	v_xor_b32_e32 v227, 32, v133
	v_lshlrev_b32_e32 v227, 2, v227
	s_lshl_b32 s46, s11, 11
	s_lshl_b32 s47, s11, 12
	s_add_u32 s47, s47, 0x2000
	s_waitcnt lgkmcnt(0)
	s_movk_i32 s2, 0x600
.Latt16_mod:
	s_cmp_ge_u32 s2, s41
	s_cbranch_scc0 .Latt16_mod_done
	s_sub_u32 s2, s2, s41
	s_branch .Latt16_mod
.Latt16_mod_done:
	s_and_b32 s3, s41, 1
	s_or_b32 s49, s2, s3
	s_lshr_b32 s54, s41, 1
	s_mov_b32 s40, s74
	s_mov_b32 s55, 0
.Latt16_item:
	s_cmp_lg_u32 s49, 0
	s_cbranch_scc1 .Latt16_plain
	s_cmp_ge_u32 s74, s54
	s_cselect_b32 s3, 1, 0
	s_cselect_b32 s2, s54, 0
	s_sub_u32 s2, s74, s2
	s_mul_i32 s4, s54, s55
	s_add_u32 s2, s2, s4
	s_branch .Latt16_dec
.Latt16_plain:
	s_and_b32 s2, s40, 63
	s_lshr_b32 s4, s40, 7
	s_lshl_b32 s4, s4, 6
	s_or_b32 s2, s2, s4
	s_bfe_u32 s3, s40, 0x10006
.Latt16_dec:
	s_and_b32 s4, s2, 63
	s_lshr_b32 s5, s2, 6
	s_cmp_ge_u32 s5, 6
	s_cselect_b32 s6, 1, 0
	s_mul_i32 s7, s6, 6
	s_sub_u32 s7, s5, s7
	s_mul_i32 s8, s6, 0x2100
	s_lshl_b32 s9, s4, 7
	s_add_u32 s8, s8, s9
	s_lshl_b32 s9, s11, 5
	s_add_u32 s8, s8, s9
	s_add_u32 s8, s8, 0x100
	s_mul_i32 s8, s8, 0x600
	s_lshl_b32 s9, s7, 8
	s_lshl_b32 s10, s3, 7
	s_add_u32 s12, s9, s10
	s_add_u32 s13, s8, s12
	s_add_u32 s52, s94, s13
	s_addc_u32 s53, s95, 0
	s_add_u32 s52, s52, 0x4510000
	s_addc_u32 s53, s53, 0
	s_mul_i32 s13, s3, 0x18c0000
	s_add_u32 s13, s13, s8
	s_add_u32 s13, s13, s9
	s_add_u32 s50, s94, s13
	s_addc_u32 s51, s95, 0
	s_add_u32 s50, s50, 0x9fd0000
	s_addc_u32 s51, s51, 0
	s_mul_i32 s13, s6, 0xc60000
	s_add_u32 s13, s13, s12
	s_add_u32 s42, s94, s13
	s_addc_u32 s43, s95, 0
	s_add_u32 s42, s42, 0x5dd0000
	s_addc_u32 s43, s43, 0
	s_mul_i32 s13, s6, 0x300
	s_lshl_b32 s9, s7, 7
	s_add_u32 s13, s13, s9
	s_mul_i32 s13, s13, 0x4200
	s_add_u32 s44, s94, s13
	s_addc_u32 s45, s95, 0
	s_add_u32 s44, s44, 0x7690000
	s_addc_u32 s45, s45, 0
	global_load_dwordx4 v[100:103], v224, s[52:53]
	global_load_dwordx4 v[104:107], v224, s[52:53] offset:64
	global_load_dwordx4 v[108:111], v225, s[52:53]
	global_load_dwordx4 v[112:115], v225, s[52:53] offset:64
	s_barrier
	s_mov_b32 m0, s46
	s_nop 0
	global_load_lds_dwordx4 v216, s[42:43]
	s_add_u32 m0, s46, 0x400
	s_nop 0
	global_load_lds_dwordx4 v217, s[42:43]
	s_mov_b32 m0, s47
	s_nop 0
	global_load_lds_dwordx4 v218, s[44:45]
	s_add_u32 m0, s47, 0x400
	s_nop 0
	global_load_lds_dwordx4 v219, s[44:45]
	s_add_u32 m0, s47, 0x800
	s_nop 0
	global_load_lds_dwordx4 v220, s[44:45]
	s_add_u32 m0, s47, 0xc00
	s_nop 0
	global_load_lds_dwordx4 v221, s[44:45]
	s_add_u32 s42, s42, 0x18000
	s_addc_u32 s43, s43, 0
	s_add_u32 s44, s44, 0x80
	s_addc_u32 s45, s45, 0
	v_mov_b32_e32 v4, 0
	v_mov_b32_e32 v5, 0
	v_mov_b32_e32 v6, 0
	v_mov_b32_e32 v7, 0
	v_mov_b32_e32 v8, 0
	v_mov_b32_e32 v9, 0
	v_mov_b32_e32 v10, 0
	v_mov_b32_e32 v11, 0
	v_mov_b32_e32 v12, 0
	v_mov_b32_e32 v13, 0
	v_mov_b32_e32 v14, 0
	v_mov_b32_e32 v15, 0
	v_mov_b32_e32 v16, 0
	v_mov_b32_e32 v17, 0
	v_mov_b32_e32 v18, 0
	v_mov_b32_e32 v19, 0
	v_mov_b32_e32 v20, 0
	v_mov_b32_e32 v21, 0
	v_mov_b32_e32 v22, 0
	v_mov_b32_e32 v23, 0
	v_mov_b32_e32 v24, 0
	v_mov_b32_e32 v25, 0
	v_mov_b32_e32 v26, 0
	v_mov_b32_e32 v27, 0
	v_mov_b32_e32 v28, 0
	v_mov_b32_e32 v29, 0
	v_mov_b32_e32 v30, 0
	v_mov_b32_e32 v31, 0
	v_mov_b32_e32 v32, 0
	v_mov_b32_e32 v33, 0
	v_mov_b32_e32 v34, 0
	v_mov_b32_e32 v35, 0
	v_mov_b32_e32 v36, 0
	v_mov_b32_e32 v37, 0
	v_mov_b32_e32 v38, 0
	v_mov_b32_e32 v39, 0
	v_mov_b32_e32 v40, 0
	v_mov_b32_e32 v41, 0
	v_mov_b32_e32 v42, 0
	v_mov_b32_e32 v43, 0
	v_mov_b32_e32 v44, 0
	v_mov_b32_e32 v45, 0
	v_mov_b32_e32 v46, 0
	v_mov_b32_e32 v47, 0
	v_mov_b32_e32 v48, 0
	v_mov_b32_e32 v49, 0
	v_mov_b32_e32 v50, 0
	v_mov_b32_e32 v51, 0
	v_mov_b32_e32 v52, 0
	v_mov_b32_e32 v53, 0
	v_mov_b32_e32 v54, 0
	v_mov_b32_e32 v55, 0
	v_mov_b32_e32 v56, 0
	v_mov_b32_e32 v57, 0
	v_mov_b32_e32 v58, 0
	v_mov_b32_e32 v59, 0
	v_mov_b32_e32 v60, 0
	v_mov_b32_e32 v61, 0
	v_mov_b32_e32 v62, 0
	v_mov_b32_e32 v63, 0
	v_mov_b32_e32 v64, 0
	v_mov_b32_e32 v65, 0
	v_mov_b32_e32 v66, 0
	v_mov_b32_e32 v67, 0
	v_mov_b32_e32 v116, 0
	v_mov_b32_e32 v117, 0
	v_mov_b32_e32 v118, 0
	v_mov_b32_e32 v119, 0
	v_mov_b32_e32 v120, 0
	v_mov_b32_e32 v121, 0
	v_mov_b32_e32 v122, 0
	v_mov_b32_e32 v123, 0
	v_mov_b32_e32 v126, 0
	v_mov_b32_e32 v127, 0
	s_waitcnt vmcnt(0)
	s_barrier
	ds_read_b128 v[148:151], v222 offset:0
	ds_read_b128 v[152:155], v222 offset:2048
	s_add_u32 m0, s46, 0x6000
	ds_read_b128 v[156:159], v222 offset:4096
	global_load_lds_dwordx4 v216, s[42:43]
	s_add_u32 m0, s46, 0x6400
	ds_read_b128 v[160:163], v222 offset:6144
	global_load_lds_dwordx4 v217, s[42:43]
	s_add_u32 m0, s47, 0x6000
	ds_read_b128 v[164:167], v223 offset:0
	global_load_lds_dwordx4 v218, s[44:45]
	s_add_u32 m0, s47, 0x6400
	ds_read_b128 v[168:171], v223 offset:2048
	global_load_lds_dwordx4 v219, s[44:45]
	s_add_u32 m0, s47, 0x6800
	ds_read_b128 v[172:175], v223 offset:4096
	global_load_lds_dwordx4 v220, s[44:45]
	s_add_u32 m0, s47, 0x6c00
	ds_read_b128 v[176:179], v223 offset:6144
	global_load_lds_dwordx4 v221, s[44:45]
	s_add_u32 s42, s42, 0x18000
	s_addc_u32 s43, s43, 0
	s_add_u32 s44, s44, 0x80
	s_addc_u32 s45, s45, 0
	ds_read_b128 v[180:183], v222 offset:8192
	ds_read_b128 v[184:187], v222 offset:10240
	ds_read_b128 v[188:191], v222 offset:12288
	ds_read_b128 v[192:195], v222 offset:14336
	s_waitcnt lgkmcnt(11)
	v_mfma_f32_16x16x32_bf16 v[68:71], v[148:151], v[100:103], v[116:119]
	v_mfma_f32_16x16x32_bf16 v[76:79], v[148:151], v[108:111], v[120:123]
	ds_read_b128 v[148:151], v222 offset:16384
	s_waitcnt lgkmcnt(11)
	v_mfma_f32_16x16x32_bf16 v[72:75], v[152:155], v[100:103], v[116:119]
	v_mfma_f32_16x16x32_bf16 v[80:83], v[152:155], v[108:111], v[120:123]
	ds_read_b128 v[152:155], v222 offset:18432
	s_waitcnt lgkmcnt(11)
	v_mfma_f32_16x16x32_bf16 v[84:87], v[156:159], v[100:103], v[116:119]
	v_mfma_f32_16x16x32_bf16 v[92:95], v[156:159], v[108:111], v[120:123]
	ds_read_b128 v[156:159], v222 offset:20480
	s_waitcnt lgkmcnt(11)
	v_mfma_f32_16x16x32_bf16 v[88:91], v[160:163], v[100:103], v[116:119]
	v_mfma_f32_16x16x32_bf16 v[96:99], v[160:163], v[108:111], v[120:123]
	ds_read_b128 v[160:163], v222 offset:22528
	s_waitcnt lgkmcnt(11)
	v_mfma_f32_16x16x32_bf16 v[68:71], v[164:167], v[104:107], v[68:71]
	v_mfma_f32_16x16x32_bf16 v[76:79], v[164:167], v[112:115], v[76:79]
	ds_read_b128 v[164:167], v223 offset:8192
	s_waitcnt lgkmcnt(11)
	v_mfma_f32_16x16x32_bf16 v[72:75], v[168:171], v[104:107], v[72:75]
	v_mfma_f32_16x16x32_bf16 v[80:83], v[168:171], v[112:115], v[80:83]
	ds_read_b128 v[168:171], v223 offset:10240
	s_waitcnt lgkmcnt(11)
	v_mfma_f32_16x16x32_bf16 v[84:87], v[172:175], v[104:107], v[84:87]
	v_mfma_f32_16x16x32_bf16 v[92:95], v[172:175], v[112:115], v[92:95]
	ds_read_b128 v[172:175], v223 offset:12288
	s_waitcnt lgkmcnt(11)
	v_mfma_f32_16x16x32_bf16 v[88:91], v[176:179], v[104:107], v[88:91]
	v_mfma_f32_16x16x32_bf16 v[96:99], v[176:179], v[112:115], v[96:99]
	ds_read_b128 v[176:179], v223 offset:14336
	s_nop 7
	v_max3_f32 v200, v68, v69, v70
	v_max3_f32 v201, v71, v72, v73
	v_max3_f32 v202, v74, v75, v84
	v_max3_f32 v203, v85, v86, v87
	v_max3_f32 v204, v88, v89, v90
	v_max3_f32 v200, v200, v201, v91
	v_max3_f32 v202, v202, v203, v204
	v_max_f32_e32 v196, v200, v202
	v_max3_f32 v205, v76, v77, v78
	v_max3_f32 v206, v79, v80, v81
	v_max3_f32 v207, v82, v83, v92
	v_max3_f32 v208, v93, v94, v95
	v_max3_f32 v209, v96, v97, v98
	v_max3_f32 v205, v205, v206, v99
	v_max3_f32 v207, v207, v208, v209
	v_max_f32_e32 v197, v205, v207
	v_max_f32_e32 v198, v196, v197
	ds_bpermute_b32 v199, v226, v196
	s_waitcnt lgkmcnt(0)
	v_max_f32_e32 v196, v196, v199
	ds_bpermute_b32 v199, v227, v196
	s_waitcnt lgkmcnt(0)
	v_max_f32_e32 v196, v196, v199
	ds_bpermute_b32 v199, v226, v197
	s_waitcnt lgkmcnt(0)
	v_max_f32_e32 v197, v197, v199
	ds_bpermute_b32 v199, v227, v197
	s_waitcnt lgkmcnt(0)
	v_max_f32_e32 v197, v197, v199
	v_sub_f32_e32 v68, v68, v196
	v_sub_f32_e32 v69, v69, v196
	v_sub_f32_e32 v70, v70, v196
	v_sub_f32_e32 v71, v71, v196
	v_sub_f32_e32 v72, v72, v196
	v_sub_f32_e32 v73, v73, v196
	v_sub_f32_e32 v74, v74, v196
	v_sub_f32_e32 v75, v75, v196
	v_sub_f32_e32 v84, v84, v196
	v_sub_f32_e32 v85, v85, v196
	v_sub_f32_e32 v86, v86, v196
	v_sub_f32_e32 v87, v87, v196
	v_sub_f32_e32 v88, v88, v196
	v_sub_f32_e32 v89, v89, v196
	v_sub_f32_e32 v90, v90, v196
	v_sub_f32_e32 v91, v91, v196
	v_mov_b32_e32 v124, v196
	v_sub_f32_e32 v116, 0, v124
	v_mov_b32_e32 v117, v116
	v_mov_b32_e32 v118, v116
	v_mov_b32_e32 v119, v116
	v_sub_f32_e32 v76, v76, v197
	v_sub_f32_e32 v77, v77, v197
	v_sub_f32_e32 v78, v78, v197
	v_sub_f32_e32 v79, v79, v197
	v_sub_f32_e32 v80, v80, v197
	v_sub_f32_e32 v81, v81, v197
	v_sub_f32_e32 v82, v82, v197
	v_sub_f32_e32 v83, v83, v197
	v_sub_f32_e32 v92, v92, v197
	v_sub_f32_e32 v93, v93, v197
	v_sub_f32_e32 v94, v94, v197
	v_sub_f32_e32 v95, v95, v197
	v_sub_f32_e32 v96, v96, v197
	v_sub_f32_e32 v97, v97, v197
	v_sub_f32_e32 v98, v98, v197
	v_sub_f32_e32 v99, v99, v197
	v_mov_b32_e32 v125, v197
	v_sub_f32_e32 v120, 0, v125
	v_mov_b32_e32 v121, v120
	v_mov_b32_e32 v122, v120
	v_mov_b32_e32 v123, v120
	v_exp_f32_e32 v68, v68
	v_exp_f32_e32 v69, v69
	v_exp_f32_e32 v70, v70
	v_exp_f32_e32 v71, v71
	v_exp_f32_e32 v72, v72
	v_exp_f32_e32 v73, v73
	v_exp_f32_e32 v74, v74
	v_exp_f32_e32 v75, v75
	v_add_f32_e32 v228, v68, v69
	v_add_f32_e32 v228, v228, v70
	v_add_f32_e32 v228, v228, v71
	v_add_f32_e32 v228, v228, v72
	v_add_f32_e32 v228, v228, v73
	v_add_f32_e32 v228, v228, v74
	v_add_f32_e32 v228, v228, v75
	v_cvt_pk_bf16_f32 v68, v68, v69
	v_cvt_pk_bf16_f32 v69, v70, v71
	v_cvt_pk_bf16_f32 v70, v72, v73
	v_cvt_pk_bf16_f32 v71, v74, v75
	v_exp_f32_e32 v76, v76
	v_exp_f32_e32 v77, v77
	v_exp_f32_e32 v78, v78
	v_exp_f32_e32 v79, v79
	v_exp_f32_e32 v80, v80
	v_exp_f32_e32 v81, v81
	v_exp_f32_e32 v82, v82
	v_exp_f32_e32 v83, v83
	v_add_f32_e32 v229, v76, v77
	v_add_f32_e32 v229, v229, v78
	v_add_f32_e32 v229, v229, v79
	v_add_f32_e32 v229, v229, v80
	v_add_f32_e32 v229, v229, v81
	v_add_f32_e32 v229, v229, v82
	v_add_f32_e32 v229, v229, v83
	v_cvt_pk_bf16_f32 v76, v76, v77
	v_cvt_pk_bf16_f32 v77, v78, v79
	v_cvt_pk_bf16_f32 v78, v80, v81
	v_cvt_pk_bf16_f32 v79, v82, v83
	v_exp_f32_e32 v84, v84
	v_exp_f32_e32 v85, v85
	s_waitcnt lgkmcnt(11)
	v_mfma_f32_16x16x32_bf16 v[4:7], v[180:183], v[68:71], v[4:7]
	v_exp_f32_e32 v86, v86
	v_exp_f32_e32 v87, v87
	v_mfma_f32_16x16x32_bf16 v[8:11], v[180:183], v[76:79], v[8:11]
	v_exp_f32_e32 v88, v88
	v_exp_f32_e32 v89, v89
	ds_read_b128 v[180:183], v223 offset:16384
	s_waitcnt lgkmcnt(11)
	v_mfma_f32_16x16x32_bf16 v[12:15], v[184:187], v[68:71], v[12:15]
	v_exp_f32_e32 v90, v90
	v_exp_f32_e32 v91, v91
	v_mfma_f32_16x16x32_bf16 v[16:19], v[184:187], v[76:79], v[16:19]
	v_add_f32_e32 v228, v228, v84
	v_add_f32_e32 v228, v228, v85
	v_add_f32_e32 v228, v228, v86
	v_add_f32_e32 v228, v228, v87
	ds_read_b128 v[184:187], v223 offset:18432
	s_waitcnt lgkmcnt(11)
	v_mfma_f32_16x16x32_bf16 v[20:23], v[188:191], v[68:71], v[20:23]
	v_add_f32_e32 v228, v228, v88
	v_add_f32_e32 v228, v228, v89
	v_add_f32_e32 v228, v228, v90
	v_add_f32_e32 v228, v228, v91
	v_mfma_f32_16x16x32_bf16 v[24:27], v[188:191], v[76:79], v[24:27]
	v_cvt_pk_bf16_f32 v84, v84, v85
	v_cvt_pk_bf16_f32 v85, v86, v87
	v_cvt_pk_bf16_f32 v86, v88, v89
	v_cvt_pk_bf16_f32 v87, v90, v91
	ds_read_b128 v[188:191], v223 offset:20480
	s_waitcnt lgkmcnt(11)
	v_mfma_f32_16x16x32_bf16 v[28:31], v[192:195], v[68:71], v[28:31]
	v_exp_f32_e32 v92, v92
	v_exp_f32_e32 v93, v93
	v_mfma_f32_16x16x32_bf16 v[32:35], v[192:195], v[76:79], v[32:35]
	v_exp_f32_e32 v94, v94
	v_exp_f32_e32 v95, v95
	ds_read_b128 v[192:195], v223 offset:22528
	s_waitcnt lgkmcnt(11)
	v_mfma_f32_16x16x32_bf16 v[36:39], v[148:151], v[68:71], v[36:39]
	v_exp_f32_e32 v96, v96
	v_exp_f32_e32 v97, v97
	v_mfma_f32_16x16x32_bf16 v[40:43], v[148:151], v[76:79], v[40:43]
	v_exp_f32_e32 v98, v98
	v_exp_f32_e32 v99, v99
	s_waitcnt lgkmcnt(10)
	v_mfma_f32_16x16x32_bf16 v[44:47], v[152:155], v[68:71], v[44:47]
	v_add_f32_e32 v229, v229, v92
	v_add_f32_e32 v229, v229, v93
	v_add_f32_e32 v229, v229, v94
	v_add_f32_e32 v229, v229, v95
	v_mfma_f32_16x16x32_bf16 v[48:51], v[152:155], v[76:79], v[48:51]
	v_add_f32_e32 v229, v229, v96
	v_add_f32_e32 v229, v229, v97
	v_add_f32_e32 v229, v229, v98
	v_add_f32_e32 v229, v229, v99
	s_waitcnt lgkmcnt(9)
	v_mfma_f32_16x16x32_bf16 v[52:55], v[156:159], v[68:71], v[52:55]
	v_cvt_pk_bf16_f32 v92, v92, v93
	v_cvt_pk_bf16_f32 v93, v94, v95
	v_cvt_pk_bf16_f32 v94, v96, v97
	v_cvt_pk_bf16_f32 v95, v98, v99
	v_mfma_f32_16x16x32_bf16 v[56:59], v[156:159], v[76:79], v[56:59]
	s_waitcnt lgkmcnt(8)
	v_mfma_f32_16x16x32_bf16 v[60:63], v[160:163], v[68:71], v[60:63]
	v_mfma_f32_16x16x32_bf16 v[64:67], v[160:163], v[76:79], v[64:67]
	s_nop 1
	s_waitcnt lgkmcnt(7)
	v_mfma_f32_16x16x32_bf16 v[4:7], v[164:167], v[84:87], v[4:7]
	v_mfma_f32_16x16x32_bf16 v[8:11], v[164:167], v[92:95], v[8:11]
	s_waitcnt lgkmcnt(6)
	v_mfma_f32_16x16x32_bf16 v[12:15], v[168:171], v[84:87], v[12:15]
	v_mfma_f32_16x16x32_bf16 v[16:19], v[168:171], v[92:95], v[16:19]
	s_waitcnt lgkmcnt(5)
	v_mfma_f32_16x16x32_bf16 v[20:23], v[172:175], v[84:87], v[20:23]
	v_mfma_f32_16x16x32_bf16 v[24:27], v[172:175], v[92:95], v[24:27]
	s_waitcnt lgkmcnt(4)
	v_mfma_f32_16x16x32_bf16 v[28:31], v[176:179], v[84:87], v[28:31]
	v_mfma_f32_16x16x32_bf16 v[32:35], v[176:179], v[92:95], v[32:35]
	s_waitcnt lgkmcnt(3)
	v_mfma_f32_16x16x32_bf16 v[36:39], v[180:183], v[84:87], v[36:39]
	v_mfma_f32_16x16x32_bf16 v[40:43], v[180:183], v[92:95], v[40:43]
	s_waitcnt lgkmcnt(2)
	v_mfma_f32_16x16x32_bf16 v[44:47], v[184:187], v[84:87], v[44:47]
	v_mfma_f32_16x16x32_bf16 v[48:51], v[184:187], v[92:95], v[48:51]
	s_waitcnt lgkmcnt(1)
	v_mfma_f32_16x16x32_bf16 v[52:55], v[188:191], v[84:87], v[52:55]
	v_mfma_f32_16x16x32_bf16 v[56:59], v[188:191], v[92:95], v[56:59]
	s_waitcnt lgkmcnt(0)
	v_mfma_f32_16x16x32_bf16 v[60:63], v[192:195], v[84:87], v[60:63]
	v_mfma_f32_16x16x32_bf16 v[64:67], v[192:195], v[92:95], v[64:67]
	v_add_f32_e32 v126, v126, v228
	v_add_f32_e32 v127, v127, v229
	s_movk_i32 s48, 0x41
.Latt16_loop:
	s_waitcnt vmcnt(0)
	s_barrier
	ds_read_b128 v[148:151], v222 offset:24576
	ds_read_b128 v[152:155], v222 offset:26624
	s_mov_b32 m0, s46
	ds_read_b128 v[156:159], v222 offset:28672
	global_load_lds_dwordx4 v216, s[42:43]
	s_add_u32 m0, s46, 0x400
	ds_read_b128 v[160:163], v222 offset:30720
	global_load_lds_dwordx4 v217, s[42:43]
	s_mov_b32 m0, s47
	ds_read_b128 v[164:167], v223 offset:24576
	global_load_lds_dwordx4 v218, s[44:45]
	s_add_u32 m0, s47, 0x400
	ds_read_b128 v[168:171], v223 offset:26624
	global_load_lds_dwordx4 v219, s[44:45]
	s_add_u32 m0, s47, 0x800
	ds_read_b128 v[172:175], v223 offset:28672
	global_load_lds_dwordx4 v220, s[44:45]
	s_add_u32 m0, s47, 0xc00
	ds_read_b128 v[176:179], v223 offset:30720
	global_load_lds_dwordx4 v221, s[44:45]
	s_add_u32 s42, s42, 0x18000
	s_addc_u32 s43, s43, 0
	s_add_u32 s44, s44, 0x80
	s_addc_u32 s45, s45, 0
	ds_read_b128 v[180:183], v222 offset:32768
	ds_read_b128 v[184:187], v222 offset:34816
	ds_read_b128 v[188:191], v222 offset:36864
	ds_read_b128 v[192:195], v222 offset:38912
	s_waitcnt lgkmcnt(11)
	v_mfma_f32_16x16x32_bf16 v[68:71], v[148:151], v[100:103], v[116:119]
	v_mfma_f32_16x16x32_bf16 v[76:79], v[148:151], v[108:111], v[120:123]
	ds_read_b128 v[148:151], v222 offset:40960
	s_waitcnt lgkmcnt(11)
	v_mfma_f32_16x16x32_bf16 v[72:75], v[152:155], v[100:103], v[116:119]
	v_mfma_f32_16x16x32_bf16 v[80:83], v[152:155], v[108:111], v[120:123]
	ds_read_b128 v[152:155], v222 offset:43008
	s_waitcnt lgkmcnt(11)
	v_mfma_f32_16x16x32_bf16 v[84:87], v[156:159], v[100:103], v[116:119]
	v_mfma_f32_16x16x32_bf16 v[92:95], v[156:159], v[108:111], v[120:123]
	ds_read_b128 v[156:159], v222 offset:45056
	s_waitcnt lgkmcnt(11)
	v_mfma_f32_16x16x32_bf16 v[88:91], v[160:163], v[100:103], v[116:119]
	v_mfma_f32_16x16x32_bf16 v[96:99], v[160:163], v[108:111], v[120:123]
	ds_read_b128 v[160:163], v222 offset:47104
	s_waitcnt lgkmcnt(11)
	v_mfma_f32_16x16x32_bf16 v[68:71], v[164:167], v[104:107], v[68:71]
	v_mfma_f32_16x16x32_bf16 v[76:79], v[164:167], v[112:115], v[76:79]
	ds_read_b128 v[164:167], v223 offset:32768
	s_waitcnt lgkmcnt(11)
	v_mfma_f32_16x16x32_bf16 v[72:75], v[168:171], v[104:107], v[72:75]
	v_mfma_f32_16x16x32_bf16 v[80:83], v[168:171], v[112:115], v[80:83]
	ds_read_b128 v[168:171], v223 offset:34816
	s_waitcnt lgkmcnt(11)
	v_mfma_f32_16x16x32_bf16 v[84:87], v[172:175], v[104:107], v[84:87]
	v_mfma_f32_16x16x32_bf16 v[92:95], v[172:175], v[112:115], v[92:95]
	ds_read_b128 v[172:175], v223 offset:36864
	s_waitcnt lgkmcnt(11)
	v_mfma_f32_16x16x32_bf16 v[88:91], v[176:179], v[104:107], v[88:91]
	v_mfma_f32_16x16x32_bf16 v[96:99], v[176:179], v[112:115], v[96:99]
	ds_read_b128 v[176:179], v223 offset:38912
	s_nop 7
	v_max3_f32 v200, v68, v69, v70
	v_max3_f32 v201, v71, v72, v73
	v_max3_f32 v202, v74, v75, v84
	v_max3_f32 v203, v85, v86, v87
	v_max3_f32 v204, v88, v89, v90
	v_max3_f32 v200, v200, v201, v91
	v_max3_f32 v202, v202, v203, v204
	v_max_f32_e32 v196, v200, v202
	v_max3_f32 v205, v76, v77, v78
	v_max3_f32 v206, v79, v80, v81
	v_max3_f32 v207, v82, v83, v92
	v_max3_f32 v208, v93, v94, v95
	v_max3_f32 v209, v96, v97, v98
	v_max3_f32 v205, v205, v206, v99
	v_max3_f32 v207, v207, v208, v209
	v_max_f32_e32 v197, v205, v207
	v_max_f32_e32 v198, v196, v197
	v_cmp_lt_f32_e32 vcc, 0, v198
	s_cbranch_vccnz .Latt16_resc_a
.Latt16_cont_a:
	v_exp_f32_e32 v68, v68
	v_exp_f32_e32 v69, v69
	v_exp_f32_e32 v70, v70
	v_exp_f32_e32 v71, v71
	v_exp_f32_e32 v72, v72
	v_exp_f32_e32 v73, v73
	v_exp_f32_e32 v74, v74
	v_exp_f32_e32 v75, v75
	v_add_f32_e32 v228, v68, v69
	v_add_f32_e32 v228, v228, v70
	v_add_f32_e32 v228, v228, v71
	v_add_f32_e32 v228, v228, v72
	v_add_f32_e32 v228, v228, v73
	v_add_f32_e32 v228, v228, v74
	v_add_f32_e32 v228, v228, v75
	v_cvt_pk_bf16_f32 v68, v68, v69
	v_cvt_pk_bf16_f32 v69, v70, v71
	v_cvt_pk_bf16_f32 v70, v72, v73
	v_cvt_pk_bf16_f32 v71, v74, v75
	v_exp_f32_e32 v76, v76
	v_exp_f32_e32 v77, v77
	v_exp_f32_e32 v78, v78
	v_exp_f32_e32 v79, v79
	v_exp_f32_e32 v80, v80
	v_exp_f32_e32 v81, v81
	v_exp_f32_e32 v82, v82
	v_exp_f32_e32 v83, v83
	v_add_f32_e32 v229, v76, v77
	v_add_f32_e32 v229, v229, v78
	v_add_f32_e32 v229, v229, v79
	v_add_f32_e32 v229, v229, v80
	v_add_f32_e32 v229, v229, v81
	v_add_f32_e32 v229, v229, v82
	v_add_f32_e32 v229, v229, v83
	v_cvt_pk_bf16_f32 v76, v76, v77
	v_cvt_pk_bf16_f32 v77, v78, v79
	v_cvt_pk_bf16_f32 v78, v80, v81
	v_cvt_pk_bf16_f32 v79, v82, v83
	v_exp_f32_e32 v84, v84
	v_exp_f32_e32 v85, v85
	s_waitcnt lgkmcnt(11)
	v_mfma_f32_16x16x32_bf16 v[4:7], v[180:183], v[68:71], v[4:7]
	v_exp_f32_e32 v86, v86
	v_exp_f32_e32 v87, v87
	v_mfma_f32_16x16x32_bf16 v[8:11], v[180:183], v[76:79], v[8:11]
	v_exp_f32_e32 v88, v88
	v_exp_f32_e32 v89, v89
	ds_read_b128 v[180:183], v223 offset:40960
	s_waitcnt lgkmcnt(11)
	v_mfma_f32_16x16x32_bf16 v[12:15], v[184:187], v[68:71], v[12:15]
	v_exp_f32_e32 v90, v90
	v_exp_f32_e32 v91, v91
	v_mfma_f32_16x16x32_bf16 v[16:19], v[184:187], v[76:79], v[16:19]
	v_add_f32_e32 v228, v228, v84
	v_add_f32_e32 v228, v228, v85
	v_add_f32_e32 v228, v228, v86
	v_add_f32_e32 v228, v228, v87
	ds_read_b128 v[184:187], v223 offset:43008
	s_waitcnt lgkmcnt(11)
	v_mfma_f32_16x16x32_bf16 v[20:23], v[188:191], v[68:71], v[20:23]
	v_add_f32_e32 v228, v228, v88
	v_add_f32_e32 v228, v228, v89
	v_add_f32_e32 v228, v228, v90
	v_add_f32_e32 v228, v228, v91
	v_mfma_f32_16x16x32_bf16 v[24:27], v[188:191], v[76:79], v[24:27]
	v_cvt_pk_bf16_f32 v84, v84, v85
	v_cvt_pk_bf16_f32 v85, v86, v87
	v_cvt_pk_bf16_f32 v86, v88, v89
	v_cvt_pk_bf16_f32 v87, v90, v91
	ds_read_b128 v[188:191], v223 offset:45056
	s_waitcnt lgkmcnt(11)
	v_mfma_f32_16x16x32_bf16 v[28:31], v[192:195], v[68:71], v[28:31]
	v_exp_f32_e32 v92, v92
	v_exp_f32_e32 v93, v93
	v_mfma_f32_16x16x32_bf16 v[32:35], v[192:195], v[76:79], v[32:35]
	v_exp_f32_e32 v94, v94
	v_exp_f32_e32 v95, v95
	ds_read_b128 v[192:195], v223 offset:47104
	s_waitcnt lgkmcnt(11)
	v_mfma_f32_16x16x32_bf16 v[36:39], v[148:151], v[68:71], v[36:39]
	v_exp_f32_e32 v96, v96
	v_exp_f32_e32 v97, v97
	v_mfma_f32_16x16x32_bf16 v[40:43], v[148:151], v[76:79], v[40:43]
	v_exp_f32_e32 v98, v98
	v_exp_f32_e32 v99, v99
	s_waitcnt lgkmcnt(10)
	v_mfma_f32_16x16x32_bf16 v[44:47], v[152:155], v[68:71], v[44:47]
	v_add_f32_e32 v229, v229, v92
	v_add_f32_e32 v229, v229, v93
	v_add_f32_e32 v229, v229, v94
	v_add_f32_e32 v229, v229, v95
	v_mfma_f32_16x16x32_bf16 v[48:51], v[152:155], v[76:79], v[48:51]
	v_add_f32_e32 v229, v229, v96
	v_add_f32_e32 v229, v229, v97
	v_add_f32_e32 v229, v229, v98
	v_add_f32_e32 v229, v229, v99
	s_waitcnt lgkmcnt(9)
	v_mfma_f32_16x16x32_bf16 v[52:55], v[156:159], v[68:71], v[52:55]
	v_cvt_pk_bf16_f32 v92, v92, v93
	v_cvt_pk_bf16_f32 v93, v94, v95
	v_cvt_pk_bf16_f32 v94, v96, v97
	v_cvt_pk_bf16_f32 v95, v98, v99
	v_mfma_f32_16x16x32_bf16 v[56:59], v[156:159], v[76:79], v[56:59]
	s_waitcnt lgkmcnt(8)
	v_mfma_f32_16x16x32_bf16 v[60:63], v[160:163], v[68:71], v[60:63]
	v_mfma_f32_16x16x32_bf16 v[64:67], v[160:163], v[76:79], v[64:67]
	s_nop 1
	s_waitcnt lgkmcnt(7)
	v_mfma_f32_16x16x32_bf16 v[4:7], v[164:167], v[84:87], v[4:7]
	v_mfma_f32_16x16x32_bf16 v[8:11], v[164:167], v[92:95], v[8:11]
	s_waitcnt lgkmcnt(6)
	v_mfma_f32_16x16x32_bf16 v[12:15], v[168:171], v[84:87], v[12:15]
	v_mfma_f32_16x16x32_bf16 v[16:19], v[168:171], v[92:95], v[16:19]
	s_waitcnt lgkmcnt(5)
	v_mfma_f32_16x16x32_bf16 v[20:23], v[172:175], v[84:87], v[20:23]
	v_mfma_f32_16x16x32_bf16 v[24:27], v[172:175], v[92:95], v[24:27]
	s_waitcnt lgkmcnt(4)
	v_mfma_f32_16x16x32_bf16 v[28:31], v[176:179], v[84:87], v[28:31]
	v_mfma_f32_16x16x32_bf16 v[32:35], v[176:179], v[92:95], v[32:35]
	s_waitcnt lgkmcnt(3)
	v_mfma_f32_16x16x32_bf16 v[36:39], v[180:183], v[84:87], v[36:39]
	v_mfma_f32_16x16x32_bf16 v[40:43], v[180:183], v[92:95], v[40:43]
	s_waitcnt lgkmcnt(2)
	v_mfma_f32_16x16x32_bf16 v[44:47], v[184:187], v[84:87], v[44:47]
	v_mfma_f32_16x16x32_bf16 v[48:51], v[184:187], v[92:95], v[48:51]
	s_waitcnt lgkmcnt(1)
	v_mfma_f32_16x16x32_bf16 v[52:55], v[188:191], v[84:87], v[52:55]
	v_mfma_f32_16x16x32_bf16 v[56:59], v[188:191], v[92:95], v[56:59]
	s_waitcnt lgkmcnt(0)
	v_mfma_f32_16x16x32_bf16 v[60:63], v[192:195], v[84:87], v[60:63]
	v_mfma_f32_16x16x32_bf16 v[64:67], v[192:195], v[92:95], v[64:67]
	v_add_f32_e32 v126, v126, v228
	v_add_f32_e32 v127, v127, v229
	s_waitcnt vmcnt(0)
	s_barrier
	ds_read_b128 v[148:151], v222 offset:0
	ds_read_b128 v[152:155], v222 offset:2048
	s_add_u32 m0, s46, 0x6000
	ds_read_b128 v[156:159], v222 offset:4096
	global_load_lds_dwordx4 v216, s[42:43]
	s_add_u32 m0, s46, 0x6400
	ds_read_b128 v[160:163], v222 offset:6144
	global_load_lds_dwordx4 v217, s[42:43]
	s_add_u32 m0, s47, 0x6000
	ds_read_b128 v[164:167], v223 offset:0
	global_load_lds_dwordx4 v218, s[44:45]
	s_add_u32 m0, s47, 0x6400
	ds_read_b128 v[168:171], v223 offset:2048
	global_load_lds_dwordx4 v219, s[44:45]
	s_add_u32 m0, s47, 0x6800
	ds_read_b128 v[172:175], v223 offset:4096
	global_load_lds_dwordx4 v220, s[44:45]
	s_add_u32 m0, s47, 0x6c00
	ds_read_b128 v[176:179], v223 offset:6144
	global_load_lds_dwordx4 v221, s[44:45]
	s_add_u32 s42, s42, 0x18000
	s_addc_u32 s43, s43, 0
	s_add_u32 s44, s44, 0x80
	s_addc_u32 s45, s45, 0
	ds_read_b128 v[180:183], v222 offset:8192
	ds_read_b128 v[184:187], v222 offset:10240
	ds_read_b128 v[188:191], v222 offset:12288
	ds_read_b128 v[192:195], v222 offset:14336
	s_waitcnt lgkmcnt(11)
	v_mfma_f32_16x16x32_bf16 v[68:71], v[148:151], v[100:103], v[116:119]
	v_mfma_f32_16x16x32_bf16 v[76:79], v[148:151], v[108:111], v[120:123]
	ds_read_b128 v[148:151], v222 offset:16384
	s_waitcnt lgkmcnt(11)
	v_mfma_f32_16x16x32_bf16 v[72:75], v[152:155], v[100:103], v[116:119]
	v_mfma_f32_16x16x32_bf16 v[80:83], v[152:155], v[108:111], v[120:123]
	ds_read_b128 v[152:155], v222 offset:18432
	s_waitcnt lgkmcnt(11)
	v_mfma_f32_16x16x32_bf16 v[84:87], v[156:159], v[100:103], v[116:119]
	v_mfma_f32_16x16x32_bf16 v[92:95], v[156:159], v[108:111], v[120:123]
	ds_read_b128 v[156:159], v222 offset:20480
	s_waitcnt lgkmcnt(11)
	v_mfma_f32_16x16x32_bf16 v[88:91], v[160:163], v[100:103], v[116:119]
	v_mfma_f32_16x16x32_bf16 v[96:99], v[160:163], v[108:111], v[120:123]
	ds_read_b128 v[160:163], v222 offset:22528
	s_waitcnt lgkmcnt(11)
	v_mfma_f32_16x16x32_bf16 v[68:71], v[164:167], v[104:107], v[68:71]
	v_mfma_f32_16x16x32_bf16 v[76:79], v[164:167], v[112:115], v[76:79]
	ds_read_b128 v[164:167], v223 offset:8192
	s_waitcnt lgkmcnt(11)
	v_mfma_f32_16x16x32_bf16 v[72:75], v[168:171], v[104:107], v[72:75]
	v_mfma_f32_16x16x32_bf16 v[80:83], v[168:171], v[112:115], v[80:83]
	ds_read_b128 v[168:171], v223 offset:10240
	s_waitcnt lgkmcnt(11)
	v_mfma_f32_16x16x32_bf16 v[84:87], v[172:175], v[104:107], v[84:87]
	v_mfma_f32_16x16x32_bf16 v[92:95], v[172:175], v[112:115], v[92:95]
	ds_read_b128 v[172:175], v223 offset:12288
	s_waitcnt lgkmcnt(11)
	v_mfma_f32_16x16x32_bf16 v[88:91], v[176:179], v[104:107], v[88:91]
	v_mfma_f32_16x16x32_bf16 v[96:99], v[176:179], v[112:115], v[96:99]
	ds_read_b128 v[176:179], v223 offset:14336
	s_nop 7
	v_max3_f32 v200, v68, v69, v70
	v_max3_f32 v201, v71, v72, v73
	v_max3_f32 v202, v74, v75, v84
	v_max3_f32 v203, v85, v86, v87
	v_max3_f32 v204, v88, v89, v90
	v_max3_f32 v200, v200, v201, v91
	v_max3_f32 v202, v202, v203, v204
	v_max_f32_e32 v196, v200, v202
	v_max3_f32 v205, v76, v77, v78
	v_max3_f32 v206, v79, v80, v81
	v_max3_f32 v207, v82, v83, v92
	v_max3_f32 v208, v93, v94, v95
	v_max3_f32 v209, v96, v97, v98
	v_max3_f32 v205, v205, v206, v99
	v_max3_f32 v207, v207, v208, v209
	v_max_f32_e32 v197, v205, v207
	v_max_f32_e32 v198, v196, v197
	v_cmp_lt_f32_e32 vcc, 0, v198
	s_cbranch_vccnz .Latt16_resc_b
.Latt16_cont_b:
	v_exp_f32_e32 v68, v68
	v_exp_f32_e32 v69, v69
	v_exp_f32_e32 v70, v70
	v_exp_f32_e32 v71, v71
	v_exp_f32_e32 v72, v72
	v_exp_f32_e32 v73, v73
	v_exp_f32_e32 v74, v74
	v_exp_f32_e32 v75, v75
	v_add_f32_e32 v228, v68, v69
	v_add_f32_e32 v228, v228, v70
	v_add_f32_e32 v228, v228, v71
	v_add_f32_e32 v228, v228, v72
	v_add_f32_e32 v228, v228, v73
	v_add_f32_e32 v228, v228, v74
	v_add_f32_e32 v228, v228, v75
	v_cvt_pk_bf16_f32 v68, v68, v69
	v_cvt_pk_bf16_f32 v69, v70, v71
	v_cvt_pk_bf16_f32 v70, v72, v73
	v_cvt_pk_bf16_f32 v71, v74, v75
	v_exp_f32_e32 v76, v76
	v_exp_f32_e32 v77, v77
	v_exp_f32_e32 v78, v78
	v_exp_f32_e32 v79, v79
	v_exp_f32_e32 v80, v80
	v_exp_f32_e32 v81, v81
	v_exp_f32_e32 v82, v82
	v_exp_f32_e32 v83, v83
	v_add_f32_e32 v229, v76, v77
	v_add_f32_e32 v229, v229, v78
	v_add_f32_e32 v229, v229, v79
	v_add_f32_e32 v229, v229, v80
	v_add_f32_e32 v229, v229, v81
	v_add_f32_e32 v229, v229, v82
	v_add_f32_e32 v229, v229, v83
	v_cvt_pk_bf16_f32 v76, v76, v77
	v_cvt_pk_bf16_f32 v77, v78, v79
	v_cvt_pk_bf16_f32 v78, v80, v81
	v_cvt_pk_bf16_f32 v79, v82, v83
	v_exp_f32_e32 v84, v84
	v_exp_f32_e32 v85, v85
	s_waitcnt lgkmcnt(11)
	v_mfma_f32_16x16x32_bf16 v[4:7], v[180:183], v[68:71], v[4:7]
	v_exp_f32_e32 v86, v86
	v_exp_f32_e32 v87, v87
	v_mfma_f32_16x16x32_bf16 v[8:11], v[180:183], v[76:79], v[8:11]
	v_exp_f32_e32 v88, v88
	v_exp_f32_e32 v89, v89
	ds_read_b128 v[180:183], v223 offset:16384
	s_waitcnt lgkmcnt(11)
	v_mfma_f32_16x16x32_bf16 v[12:15], v[184:187], v[68:71], v[12:15]
	v_exp_f32_e32 v90, v90
	v_exp_f32_e32 v91, v91
	v_mfma_f32_16x16x32_bf16 v[16:19], v[184:187], v[76:79], v[16:19]
	v_add_f32_e32 v228, v228, v84
	v_add_f32_e32 v228, v228, v85
	v_add_f32_e32 v228, v228, v86
	v_add_f32_e32 v228, v228, v87
	ds_read_b128 v[184:187], v223 offset:18432
	s_waitcnt lgkmcnt(11)
	v_mfma_f32_16x16x32_bf16 v[20:23], v[188:191], v[68:71], v[20:23]
	v_add_f32_e32 v228, v228, v88
	v_add_f32_e32 v228, v228, v89
	v_add_f32_e32 v228, v228, v90
	v_add_f32_e32 v228, v228, v91
	v_mfma_f32_16x16x32_bf16 v[24:27], v[188:191], v[76:79], v[24:27]
	v_cvt_pk_bf16_f32 v84, v84, v85
	v_cvt_pk_bf16_f32 v85, v86, v87
	v_cvt_pk_bf16_f32 v86, v88, v89
	v_cvt_pk_bf16_f32 v87, v90, v91
	ds_read_b128 v[188:191], v223 offset:20480
	s_waitcnt lgkmcnt(11)
	v_mfma_f32_16x16x32_bf16 v[28:31], v[192:195], v[68:71], v[28:31]
	v_exp_f32_e32 v92, v92
	v_exp_f32_e32 v93, v93
	v_mfma_f32_16x16x32_bf16 v[32:35], v[192:195], v[76:79], v[32:35]
	v_exp_f32_e32 v94, v94
	v_exp_f32_e32 v95, v95
	ds_read_b128 v[192:195], v223 offset:22528
	s_waitcnt lgkmcnt(11)
	v_mfma_f32_16x16x32_bf16 v[36:39], v[148:151], v[68:71], v[36:39]
	v_exp_f32_e32 v96, v96
	v_exp_f32_e32 v97, v97
	v_mfma_f32_16x16x32_bf16 v[40:43], v[148:151], v[76:79], v[40:43]
	v_exp_f32_e32 v98, v98
	v_exp_f32_e32 v99, v99
	s_waitcnt lgkmcnt(10)
	v_mfma_f32_16x16x32_bf16 v[44:47], v[152:155], v[68:71], v[44:47]
	v_add_f32_e32 v229, v229, v92
	v_add_f32_e32 v229, v229, v93
	v_add_f32_e32 v229, v229, v94
	v_add_f32_e32 v229, v229, v95
	v_mfma_f32_16x16x32_bf16 v[48:51], v[152:155], v[76:79], v[48:51]
	v_add_f32_e32 v229, v229, v96
	v_add_f32_e32 v229, v229, v97
	v_add_f32_e32 v229, v229, v98
	v_add_f32_e32 v229, v229, v99
	s_waitcnt lgkmcnt(9)
	v_mfma_f32_16x16x32_bf16 v[52:55], v[156:159], v[68:71], v[52:55]
	v_cvt_pk_bf16_f32 v92, v92, v93
	v_cvt_pk_bf16_f32 v93, v94, v95
	v_cvt_pk_bf16_f32 v94, v96, v97
	v_cvt_pk_bf16_f32 v95, v98, v99
	v_mfma_f32_16x16x32_bf16 v[56:59], v[156:159], v[76:79], v[56:59]
	s_waitcnt lgkmcnt(8)
	v_mfma_f32_16x16x32_bf16 v[60:63], v[160:163], v[68:71], v[60:63]
	v_mfma_f32_16x16x32_bf16 v[64:67], v[160:163], v[76:79], v[64:67]
	s_nop 1
	s_waitcnt lgkmcnt(7)
	v_mfma_f32_16x16x32_bf16 v[4:7], v[164:167], v[84:87], v[4:7]
	v_mfma_f32_16x16x32_bf16 v[8:11], v[164:167], v[92:95], v[8:11]
	s_waitcnt lgkmcnt(6)
	v_mfma_f32_16x16x32_bf16 v[12:15], v[168:171], v[84:87], v[12:15]
	v_mfma_f32_16x16x32_bf16 v[16:19], v[168:171], v[92:95], v[16:19]
	s_waitcnt lgkmcnt(5)
	v_mfma_f32_16x16x32_bf16 v[20:23], v[172:175], v[84:87], v[20:23]
	v_mfma_f32_16x16x32_bf16 v[24:27], v[172:175], v[92:95], v[24:27]
	s_waitcnt lgkmcnt(4)
	v_mfma_f32_16x16x32_bf16 v[28:31], v[176:179], v[84:87], v[28:31]
	v_mfma_f32_16x16x32_bf16 v[32:35], v[176:179], v[92:95], v[32:35]
	s_waitcnt lgkmcnt(3)
	v_mfma_f32_16x16x32_bf16 v[36:39], v[180:183], v[84:87], v[36:39]
	v_mfma_f32_16x16x32_bf16 v[40:43], v[180:183], v[92:95], v[40:43]
	s_waitcnt lgkmcnt(2)
	v_mfma_f32_16x16x32_bf16 v[44:47], v[184:187], v[84:87], v[44:47]
	v_mfma_f32_16x16x32_bf16 v[48:51], v[184:187], v[92:95], v[48:51]
	s_waitcnt lgkmcnt(1)
	v_mfma_f32_16x16x32_bf16 v[52:55], v[188:191], v[84:87], v[52:55]
	v_mfma_f32_16x16x32_bf16 v[56:59], v[188:191], v[92:95], v[56:59]
	s_waitcnt lgkmcnt(0)
	v_mfma_f32_16x16x32_bf16 v[60:63], v[192:195], v[84:87], v[60:63]
	v_mfma_f32_16x16x32_bf16 v[64:67], v[192:195], v[92:95], v[64:67]
	v_add_f32_e32 v126, v126, v228
	v_add_f32_e32 v127, v127, v229
	s_sub_u32 s48, s48, 1
	s_cmp_lg_u32 s48, 0
	s_cbranch_scc1 .Latt16_loop
	s_waitcnt vmcnt(0)
	s_barrier
	ds_read_b128 v[148:151], v222 offset:24576
	ds_read_b128 v[152:155], v222 offset:26624
	ds_read_b128 v[156:159], v222 offset:28672
	ds_read_b128 v[160:163], v222 offset:30720
	ds_read_b128 v[164:167], v223 offset:24576
	ds_read_b128 v[168:171], v223 offset:26624
	ds_read_b128 v[172:175], v223 offset:28672
	ds_read_b128 v[176:179], v223 offset:30720
	ds_read_b128 v[180:183], v222 offset:32768
	ds_read_b128 v[184:187], v222 offset:34816
	ds_read_b128 v[188:191], v222 offset:36864
	ds_read_b128 v[192:195], v222 offset:38912
	s_waitcnt lgkmcnt(11)
	v_mfma_f32_16x16x32_bf16 v[68:71], v[148:151], v[100:103], v[116:119]
	v_mfma_f32_16x16x32_bf16 v[76:79], v[148:151], v[108:111], v[120:123]
	ds_read_b128 v[148:151], v222 offset:40960
	s_waitcnt lgkmcnt(11)
	v_mfma_f32_16x16x32_bf16 v[72:75], v[152:155], v[100:103], v[116:119]
	v_mfma_f32_16x16x32_bf16 v[80:83], v[152:155], v[108:111], v[120:123]
	ds_read_b128 v[152:155], v222 offset:43008
	s_waitcnt lgkmcnt(11)
	v_mfma_f32_16x16x32_bf16 v[84:87], v[156:159], v[100:103], v[116:119]
	v_mfma_f32_16x16x32_bf16 v[92:95], v[156:159], v[108:111], v[120:123]
	ds_read_b128 v[156:159], v222 offset:45056
	s_waitcnt lgkmcnt(11)
	v_mfma_f32_16x16x32_bf16 v[88:91], v[160:163], v[100:103], v[116:119]
	v_mfma_f32_16x16x32_bf16 v[96:99], v[160:163], v[108:111], v[120:123]
	ds_read_b128 v[160:163], v222 offset:47104
	s_waitcnt lgkmcnt(11)
	v_mfma_f32_16x16x32_bf16 v[68:71], v[164:167], v[104:107], v[68:71]
	v_mfma_f32_16x16x32_bf16 v[76:79], v[164:167], v[112:115], v[76:79]
	ds_read_b128 v[164:167], v223 offset:32768
	s_waitcnt lgkmcnt(11)
	v_mfma_f32_16x16x32_bf16 v[72:75], v[168:171], v[104:107], v[72:75]
	v_mfma_f32_16x16x32_bf16 v[80:83], v[168:171], v[112:115], v[80:83]
	ds_read_b128 v[168:171], v223 offset:34816
	s_waitcnt lgkmcnt(11)
	v_mfma_f32_16x16x32_bf16 v[84:87], v[172:175], v[104:107], v[84:87]
	v_mfma_f32_16x16x32_bf16 v[92:95], v[172:175], v[112:115], v[92:95]
	ds_read_b128 v[172:175], v223 offset:36864
	s_waitcnt lgkmcnt(11)
	v_mfma_f32_16x16x32_bf16 v[88:91], v[176:179], v[104:107], v[88:91]
	v_mfma_f32_16x16x32_bf16 v[96:99], v[176:179], v[112:115], v[96:99]
	ds_read_b128 v[176:179], v223 offset:38912
	s_nop 7
	v_max3_f32 v200, v68, v69, v70
	v_max3_f32 v201, v71, v72, v73
	v_max3_f32 v202, v74, v75, v84
	v_max3_f32 v203, v85, v86, v87
	v_max3_f32 v204, v88, v89, v90
	v_max3_f32 v200, v200, v201, v91
	v_max3_f32 v202, v202, v203, v204
	v_max_f32_e32 v196, v200, v202
	v_max3_f32 v205, v76, v77, v78
	v_max3_f32 v206, v79, v80, v81
	v_max3_f32 v207, v82, v83, v92
	v_max3_f32 v208, v93, v94, v95
	v_max3_f32 v209, v96, v97, v98
	v_max3_f32 v205, v205, v206, v99
	v_max3_f32 v207, v207, v208, v209
	v_max_f32_e32 v197, v205, v207
	v_max_f32_e32 v198, v196, v197
	v_cmp_lt_f32_e32 vcc, 0, v198
	s_cbranch_vccnz .Latt16_resc_l
.Latt16_cont_l:
	v_exp_f32_e32 v68, v68
	v_exp_f32_e32 v69, v69
	v_exp_f32_e32 v70, v70
	v_exp_f32_e32 v71, v71
	v_exp_f32_e32 v72, v72
	v_exp_f32_e32 v73, v73
	v_exp_f32_e32 v74, v74
	v_exp_f32_e32 v75, v75
	v_add_f32_e32 v228, v68, v69
	v_add_f32_e32 v228, v228, v70
	v_add_f32_e32 v228, v228, v71
	v_add_f32_e32 v228, v228, v72
	v_add_f32_e32 v228, v228, v73
	v_add_f32_e32 v228, v228, v74
	v_add_f32_e32 v228, v228, v75
	v_cvt_pk_bf16_f32 v68, v68, v69
	v_cvt_pk_bf16_f32 v69, v70, v71
	v_cvt_pk_bf16_f32 v70, v72, v73
	v_cvt_pk_bf16_f32 v71, v74, v75
	v_exp_f32_e32 v76, v76
	v_exp_f32_e32 v77, v77
	v_exp_f32_e32 v78, v78
	v_exp_f32_e32 v79, v79
	v_exp_f32_e32 v80, v80
	v_exp_f32_e32 v81, v81
	v_exp_f32_e32 v82, v82
	v_exp_f32_e32 v83, v83
	v_add_f32_e32 v229, v76, v77
	v_add_f32_e32 v229, v229, v78
	v_add_f32_e32 v229, v229, v79
	v_add_f32_e32 v229, v229, v80
	v_add_f32_e32 v229, v229, v81
	v_add_f32_e32 v229, v229, v82
	v_add_f32_e32 v229, v229, v83
	v_cvt_pk_bf16_f32 v76, v76, v77
	v_cvt_pk_bf16_f32 v77, v78, v79
	v_cvt_pk_bf16_f32 v78, v80, v81
	v_cvt_pk_bf16_f32 v79, v82, v83
	v_exp_f32_e32 v84, v84
	v_exp_f32_e32 v85, v85
	s_waitcnt lgkmcnt(11)
	v_mfma_f32_16x16x32_bf16 v[4:7], v[180:183], v[68:71], v[4:7]
	v_exp_f32_e32 v86, v86
	v_exp_f32_e32 v87, v87
	v_mfma_f32_16x16x32_bf16 v[8:11], v[180:183], v[76:79], v[8:11]
	v_exp_f32_e32 v88, v88
	v_exp_f32_e32 v89, v89
	ds_read_b128 v[180:183], v223 offset:40960
	s_waitcnt lgkmcnt(11)
	v_mfma_f32_16x16x32_bf16 v[12:15], v[184:187], v[68:71], v[12:15]
	v_exp_f32_e32 v90, v90
	v_exp_f32_e32 v91, v91
	v_mfma_f32_16x16x32_bf16 v[16:19], v[184:187], v[76:79], v[16:19]
	v_add_f32_e32 v228, v228, v84
	v_add_f32_e32 v228, v228, v85
	v_add_f32_e32 v228, v228, v86
	v_add_f32_e32 v228, v228, v87
	ds_read_b128 v[184:187], v223 offset:43008
	s_waitcnt lgkmcnt(11)
	v_mfma_f32_16x16x32_bf16 v[20:23], v[188:191], v[68:71], v[20:23]
	v_add_f32_e32 v228, v228, v88
	v_add_f32_e32 v228, v228, v89
	v_add_f32_e32 v228, v228, v90
	v_add_f32_e32 v228, v228, v91
	v_mfma_f32_16x16x32_bf16 v[24:27], v[188:191], v[76:79], v[24:27]
	v_cvt_pk_bf16_f32 v84, v84, v85
	v_cvt_pk_bf16_f32 v85, v86, v87
	v_cvt_pk_bf16_f32 v86, v88, v89
	v_cvt_pk_bf16_f32 v87, v90, v91
	ds_read_b128 v[188:191], v223 offset:45056
	s_waitcnt lgkmcnt(11)
	v_mfma_f32_16x16x32_bf16 v[28:31], v[192:195], v[68:71], v[28:31]
	v_exp_f32_e32 v92, v92
	v_exp_f32_e32 v93, v93
	v_mfma_f32_16x16x32_bf16 v[32:35], v[192:195], v[76:79], v[32:35]
	v_exp_f32_e32 v94, v94
	v_exp_f32_e32 v95, v95
	ds_read_b128 v[192:195], v223 offset:47104
	s_waitcnt lgkmcnt(11)
	v_mfma_f32_16x16x32_bf16 v[36:39], v[148:151], v[68:71], v[36:39]
	v_exp_f32_e32 v96, v96
	v_exp_f32_e32 v97, v97
	v_mfma_f32_16x16x32_bf16 v[40:43], v[148:151], v[76:79], v[40:43]
	v_exp_f32_e32 v98, v98
	v_exp_f32_e32 v99, v99
	s_waitcnt lgkmcnt(10)
	v_mfma_f32_16x16x32_bf16 v[44:47], v[152:155], v[68:71], v[44:47]
	v_add_f32_e32 v229, v229, v92
	v_add_f32_e32 v229, v229, v93
	v_add_f32_e32 v229, v229, v94
	v_add_f32_e32 v229, v229, v95
	v_mfma_f32_16x16x32_bf16 v[48:51], v[152:155], v[76:79], v[48:51]
	v_add_f32_e32 v229, v229, v96
	v_add_f32_e32 v229, v229, v97
	v_add_f32_e32 v229, v229, v98
	v_add_f32_e32 v229, v229, v99
	s_waitcnt lgkmcnt(9)
	v_mfma_f32_16x16x32_bf16 v[52:55], v[156:159], v[68:71], v[52:55]
	v_cvt_pk_bf16_f32 v92, v92, v93
	v_cvt_pk_bf16_f32 v93, v94, v95
	v_cvt_pk_bf16_f32 v94, v96, v97
	v_cvt_pk_bf16_f32 v95, v98, v99
	v_mfma_f32_16x16x32_bf16 v[56:59], v[156:159], v[76:79], v[56:59]
	s_waitcnt lgkmcnt(8)
	v_mfma_f32_16x16x32_bf16 v[60:63], v[160:163], v[68:71], v[60:63]
	v_mfma_f32_16x16x32_bf16 v[64:67], v[160:163], v[76:79], v[64:67]
	s_nop 1
	s_waitcnt lgkmcnt(7)
	v_mfma_f32_16x16x32_bf16 v[4:7], v[164:167], v[84:87], v[4:7]
	v_mfma_f32_16x16x32_bf16 v[8:11], v[164:167], v[92:95], v[8:11]
	s_waitcnt lgkmcnt(6)
	v_mfma_f32_16x16x32_bf16 v[12:15], v[168:171], v[84:87], v[12:15]
	v_mfma_f32_16x16x32_bf16 v[16:19], v[168:171], v[92:95], v[16:19]
	s_waitcnt lgkmcnt(5)
	v_mfma_f32_16x16x32_bf16 v[20:23], v[172:175], v[84:87], v[20:23]
	v_mfma_f32_16x16x32_bf16 v[24:27], v[172:175], v[92:95], v[24:27]
	s_waitcnt lgkmcnt(4)
	v_mfma_f32_16x16x32_bf16 v[28:31], v[176:179], v[84:87], v[28:31]
	v_mfma_f32_16x16x32_bf16 v[32:35], v[176:179], v[92:95], v[32:35]
	s_waitcnt lgkmcnt(3)
	v_mfma_f32_16x16x32_bf16 v[36:39], v[180:183], v[84:87], v[36:39]
	v_mfma_f32_16x16x32_bf16 v[40:43], v[180:183], v[92:95], v[40:43]
	s_waitcnt lgkmcnt(2)
	v_mfma_f32_16x16x32_bf16 v[44:47], v[184:187], v[84:87], v[44:47]
	v_mfma_f32_16x16x32_bf16 v[48:51], v[184:187], v[92:95], v[48:51]
	s_waitcnt lgkmcnt(1)
	v_mfma_f32_16x16x32_bf16 v[52:55], v[188:191], v[84:87], v[52:55]
	v_mfma_f32_16x16x32_bf16 v[56:59], v[188:191], v[92:95], v[56:59]
	s_waitcnt lgkmcnt(0)
	v_mfma_f32_16x16x32_bf16 v[60:63], v[192:195], v[84:87], v[60:63]
	v_mfma_f32_16x16x32_bf16 v[64:67], v[192:195], v[92:95], v[64:67]
	v_add_f32_e32 v126, v126, v228
	v_add_f32_e32 v127, v127, v229
	ds_bpermute_b32 v199, v226, v126
	s_waitcnt lgkmcnt(0)
	v_add_f32_e32 v126, v126, v199
	ds_bpermute_b32 v199, v227, v126
	s_waitcnt lgkmcnt(0)
	v_add_f32_e32 v126, v126, v199
	ds_bpermute_b32 v199, v226, v127
	s_waitcnt lgkmcnt(0)
	v_add_f32_e32 v127, v127, v199
	ds_bpermute_b32 v199, v227, v127
	s_waitcnt lgkmcnt(0)
	v_add_f32_e32 v127, v127, v199
	s_nop 7
	v_rcp_f32_e32 v196, v126
	v_rcp_f32_e32 v197, v127
	v_lshlrev_b32_e32 v198, 3, v135
	v_lshlrev_b32_e32 v199, 4, v135
	v_sub_u32_e32 v200, v224, v199
	v_add_u32_e32 v200, v200, v198
	v_sub_u32_e32 v201, v225, v199
	v_add_u32_e32 v201, v201, v198
	v_mul_f32_e32 v4, v4, v196
	v_mul_f32_e32 v5, v5, v196
	v_mul_f32_e32 v6, v6, v196
	v_mul_f32_e32 v7, v7, v196
	v_cvt_pk_bf16_f32 v4, v4, v5
	v_cvt_pk_bf16_f32 v5, v6, v7
	global_store_dwordx2 v200, v[4:5], s[50:51]
	v_mul_f32_e32 v8, v8, v197
	v_mul_f32_e32 v9, v9, v197
	v_mul_f32_e32 v10, v10, v197
	v_mul_f32_e32 v11, v11, v197
	v_cvt_pk_bf16_f32 v8, v8, v9
	v_cvt_pk_bf16_f32 v9, v10, v11
	global_store_dwordx2 v201, v[8:9], s[50:51]
	v_mul_f32_e32 v12, v12, v196
	v_mul_f32_e32 v13, v13, v196
	v_mul_f32_e32 v14, v14, v196
	v_mul_f32_e32 v15, v15, v196
	v_cvt_pk_bf16_f32 v12, v12, v13
	v_cvt_pk_bf16_f32 v13, v14, v15
	global_store_dwordx2 v200, v[12:13], s[50:51] offset:32
	v_mul_f32_e32 v16, v16, v197
	v_mul_f32_e32 v17, v17, v197
	v_mul_f32_e32 v18, v18, v197
	v_mul_f32_e32 v19, v19, v197
	v_cvt_pk_bf16_f32 v16, v16, v17
	v_cvt_pk_bf16_f32 v17, v18, v19
	global_store_dwordx2 v201, v[16:17], s[50:51] offset:32
	v_mul_f32_e32 v20, v20, v196
	v_mul_f32_e32 v21, v21, v196
	v_mul_f32_e32 v22, v22, v196
	v_mul_f32_e32 v23, v23, v196
	v_cvt_pk_bf16_f32 v20, v20, v21
	v_cvt_pk_bf16_f32 v21, v22, v23
	global_store_dwordx2 v200, v[20:21], s[50:51] offset:64
	v_mul_f32_e32 v24, v24, v197
	v_mul_f32_e32 v25, v25, v197
	v_mul_f32_e32 v26, v26, v197
	v_mul_f32_e32 v27, v27, v197
	v_cvt_pk_bf16_f32 v24, v24, v25
	v_cvt_pk_bf16_f32 v25, v26, v27
	global_store_dwordx2 v201, v[24:25], s[50:51] offset:64
	v_mul_f32_e32 v28, v28, v196
	v_mul_f32_e32 v29, v29, v196
	v_mul_f32_e32 v30, v30, v196
	v_mul_f32_e32 v31, v31, v196
	v_cvt_pk_bf16_f32 v28, v28, v29
	v_cvt_pk_bf16_f32 v29, v30, v31
	global_store_dwordx2 v200, v[28:29], s[50:51] offset:96
	v_mul_f32_e32 v32, v32, v197
	v_mul_f32_e32 v33, v33, v197
	v_mul_f32_e32 v34, v34, v197
	v_mul_f32_e32 v35, v35, v197
	v_cvt_pk_bf16_f32 v32, v32, v33
	v_cvt_pk_bf16_f32 v33, v34, v35
	global_store_dwordx2 v201, v[32:33], s[50:51] offset:96
	v_mul_f32_e32 v36, v36, v196
	v_mul_f32_e32 v37, v37, v196
	v_mul_f32_e32 v38, v38, v196
	v_mul_f32_e32 v39, v39, v196
	v_cvt_pk_bf16_f32 v36, v36, v37
	v_cvt_pk_bf16_f32 v37, v38, v39
	global_store_dwordx2 v200, v[36:37], s[50:51] offset:128
	v_mul_f32_e32 v40, v40, v197
	v_mul_f32_e32 v41, v41, v197
	v_mul_f32_e32 v42, v42, v197
	v_mul_f32_e32 v43, v43, v197
	v_cvt_pk_bf16_f32 v40, v40, v41
	v_cvt_pk_bf16_f32 v41, v42, v43
	global_store_dwordx2 v201, v[40:41], s[50:51] offset:128
	v_mul_f32_e32 v44, v44, v196
	v_mul_f32_e32 v45, v45, v196
	v_mul_f32_e32 v46, v46, v196
	v_mul_f32_e32 v47, v47, v196
	v_cvt_pk_bf16_f32 v44, v44, v45
	v_cvt_pk_bf16_f32 v45, v46, v47
	global_store_dwordx2 v200, v[44:45], s[50:51] offset:160
	v_mul_f32_e32 v48, v48, v197
	v_mul_f32_e32 v49, v49, v197
	v_mul_f32_e32 v50, v50, v197
	v_mul_f32_e32 v51, v51, v197
	v_cvt_pk_bf16_f32 v48, v48, v49
	v_cvt_pk_bf16_f32 v49, v50, v51
	global_store_dwordx2 v201, v[48:49], s[50:51] offset:160
	v_mul_f32_e32 v52, v52, v196
	v_mul_f32_e32 v53, v53, v196
	v_mul_f32_e32 v54, v54, v196
	v_mul_f32_e32 v55, v55, v196
	v_cvt_pk_bf16_f32 v52, v52, v53
	v_cvt_pk_bf16_f32 v53, v54, v55
	global_store_dwordx2 v200, v[52:53], s[50:51] offset:192
	v_mul_f32_e32 v56, v56, v197
	v_mul_f32_e32 v57, v57, v197
	v_mul_f32_e32 v58, v58, v197
	v_mul_f32_e32 v59, v59, v197
	v_cvt_pk_bf16_f32 v56, v56, v57
	v_cvt_pk_bf16_f32 v57, v58, v59
	global_store_dwordx2 v201, v[56:57], s[50:51] offset:192
	v_mul_f32_e32 v60, v60, v196
	v_mul_f32_e32 v61, v61, v196
	v_mul_f32_e32 v62, v62, v196
	v_mul_f32_e32 v63, v63, v196
	v_cvt_pk_bf16_f32 v60, v60, v61
	v_cvt_pk_bf16_f32 v61, v62, v63
	global_store_dwordx2 v200, v[60:61], s[50:51] offset:224
	v_mul_f32_e32 v64, v64, v197
	v_mul_f32_e32 v65, v65, v197
	v_mul_f32_e32 v66, v66, v197
	v_mul_f32_e32 v67, v67, v197
	v_cvt_pk_bf16_f32 v64, v64, v65
	v_cvt_pk_bf16_f32 v65, v66, v67
	global_store_dwordx2 v201, v[64:65], s[50:51] offset:224
	s_add_u32 s55, s55, 1
	s_add_u32 s40, s40, s41
	s_cmpk_lt_u32 s40, 0x600
	s_cbranch_scc1 .Latt16_item
	s_branch .Latt16_done
.Latt16_resc_a:
	ds_bpermute_b32 v199, v226, v196
	s_waitcnt lgkmcnt(0)
	v_max_f32_e32 v196, v196, v199
	ds_bpermute_b32 v199, v227, v196
	s_waitcnt lgkmcnt(0)
	v_max_f32_e32 v196, v196, v199
	ds_bpermute_b32 v199, v226, v197
	s_waitcnt lgkmcnt(0)
	v_max_f32_e32 v197, v197, v199
	ds_bpermute_b32 v199, v227, v197
	s_waitcnt lgkmcnt(0)
	v_max_f32_e32 v197, v197, v199
	v_max_f32_e32 v208, 0, v196
	v_exp_f32_e64 v210, -v208
	v_sub_f32_e32 v68, v68, v208
	v_sub_f32_e32 v69, v69, v208
	v_sub_f32_e32 v70, v70, v208
	v_sub_f32_e32 v71, v71, v208
	v_sub_f32_e32 v72, v72, v208
	v_sub_f32_e32 v73, v73, v208
	v_sub_f32_e32 v74, v74, v208
	v_sub_f32_e32 v75, v75, v208
	v_sub_f32_e32 v84, v84, v208
	v_sub_f32_e32 v85, v85, v208
	v_sub_f32_e32 v86, v86, v208
	v_sub_f32_e32 v87, v87, v208
	v_sub_f32_e32 v88, v88, v208
	v_sub_f32_e32 v89, v89, v208
	v_sub_f32_e32 v90, v90, v208
	v_sub_f32_e32 v91, v91, v208
	v_add_f32_e32 v124, v124, v208
	v_mul_f32_e32 v126, v126, v210
	v_mul_f32_e32 v4, v4, v210
	v_mul_f32_e32 v5, v5, v210
	v_mul_f32_e32 v6, v6, v210
	v_mul_f32_e32 v7, v7, v210
	v_mul_f32_e32 v12, v12, v210
	v_mul_f32_e32 v13, v13, v210
	v_mul_f32_e32 v14, v14, v210
	v_mul_f32_e32 v15, v15, v210
	v_mul_f32_e32 v20, v20, v210
	v_mul_f32_e32 v21, v21, v210
	v_mul_f32_e32 v22, v22, v210
	v_mul_f32_e32 v23, v23, v210
	v_mul_f32_e32 v28, v28, v210
	v_mul_f32_e32 v29, v29, v210
	v_mul_f32_e32 v30, v30, v210
	v_mul_f32_e32 v31, v31, v210
	v_mul_f32_e32 v36, v36, v210
	v_mul_f32_e32 v37, v37, v210
	v_mul_f32_e32 v38, v38, v210
	v_mul_f32_e32 v39, v39, v210
	v_mul_f32_e32 v44, v44, v210
	v_mul_f32_e32 v45, v45, v210
	v_mul_f32_e32 v46, v46, v210
	v_mul_f32_e32 v47, v47, v210
	v_mul_f32_e32 v52, v52, v210
	v_mul_f32_e32 v53, v53, v210
	v_mul_f32_e32 v54, v54, v210
	v_mul_f32_e32 v55, v55, v210
	v_mul_f32_e32 v60, v60, v210
	v_mul_f32_e32 v61, v61, v210
	v_mul_f32_e32 v62, v62, v210
	v_mul_f32_e32 v63, v63, v210
	v_sub_f32_e32 v116, 0, v124
	v_mov_b32_e32 v117, v116
	v_mov_b32_e32 v118, v116
	v_mov_b32_e32 v119, v116
	v_max_f32_e32 v209, 0, v197
	v_exp_f32_e64 v211, -v209
	v_sub_f32_e32 v76, v76, v209
	v_sub_f32_e32 v77, v77, v209
	v_sub_f32_e32 v78, v78, v209
	v_sub_f32_e32 v79, v79, v209
	v_sub_f32_e32 v80, v80, v209
	v_sub_f32_e32 v81, v81, v209
	v_sub_f32_e32 v82, v82, v209
	v_sub_f32_e32 v83, v83, v209
	v_sub_f32_e32 v92, v92, v209
	v_sub_f32_e32 v93, v93, v209
	v_sub_f32_e32 v94, v94, v209
	v_sub_f32_e32 v95, v95, v209
	v_sub_f32_e32 v96, v96, v209
	v_sub_f32_e32 v97, v97, v209
	v_sub_f32_e32 v98, v98, v209
	v_sub_f32_e32 v99, v99, v209
	v_add_f32_e32 v125, v125, v209
	v_mul_f32_e32 v127, v127, v211
	v_mul_f32_e32 v8, v8, v211
	v_mul_f32_e32 v9, v9, v211
	v_mul_f32_e32 v10, v10, v211
	v_mul_f32_e32 v11, v11, v211
	v_mul_f32_e32 v16, v16, v211
	v_mul_f32_e32 v17, v17, v211
	v_mul_f32_e32 v18, v18, v211
	v_mul_f32_e32 v19, v19, v211
	v_mul_f32_e32 v24, v24, v211
	v_mul_f32_e32 v25, v25, v211
	v_mul_f32_e32 v26, v26, v211
	v_mul_f32_e32 v27, v27, v211
	v_mul_f32_e32 v32, v32, v211
	v_mul_f32_e32 v33, v33, v211
	v_mul_f32_e32 v34, v34, v211
	v_mul_f32_e32 v35, v35, v211
	v_mul_f32_e32 v40, v40, v211
	v_mul_f32_e32 v41, v41, v211
	v_mul_f32_e32 v42, v42, v211
	v_mul_f32_e32 v43, v43, v211
	v_mul_f32_e32 v48, v48, v211
	v_mul_f32_e32 v49, v49, v211
	v_mul_f32_e32 v50, v50, v211
	v_mul_f32_e32 v51, v51, v211
	v_mul_f32_e32 v56, v56, v211
	v_mul_f32_e32 v57, v57, v211
	v_mul_f32_e32 v58, v58, v211
	v_mul_f32_e32 v59, v59, v211
	v_mul_f32_e32 v64, v64, v211
	v_mul_f32_e32 v65, v65, v211
	v_mul_f32_e32 v66, v66, v211
	v_mul_f32_e32 v67, v67, v211
	v_sub_f32_e32 v120, 0, v125
	v_mov_b32_e32 v121, v120
	v_mov_b32_e32 v122, v120
	v_mov_b32_e32 v123, v120
	s_branch .Latt16_cont_a

.Latt16_done:
.LBB0_1485:
	s_cmp_lt_i32 s76, 15
	s_cselect_b64 s[2:3], -1, 0
	s_cmp_gt_i32 s77, 14
	s_cselect_b64 s[4:5], -1, 0
	s_and_b64 s[4:5], s[2:3], s[4:5]
	s_andn2_b64 vcc, exec, s[4:5]
	s_cbranch_vccnz .LBB0_1552
	s_andn2_b64 vcc, exec, s[0:1]
	s_cbranch_vccnz .LBB0_1540
	s_waitcnt vmcnt(0)
	s_waitcnt lgkmcnt(0)
	s_barrier
	s_mov_b64 s[0:1], exec
	v_readlane_b32 s4, v252, 0
	v_readlane_b32 s5, v252, 1
	s_and_b64 s[4:5], s[0:1], s[4:5]
	s_mov_b64 exec, s[4:5]
	s_cbranch_execz .LBB0_1539
	s_add_i32 s4, 0, 0x137f0
	v_mov_b32_e32 v0, s4
	s_waitcnt vmcnt(0) expcnt(0) lgkmcnt(0)
	ds_read_b32 v2, v0
	s_add_i32 s4, 0, 0x137f4
	v_mov_b32_e32 v0, s4
	ds_read_b32 v0, v0
	s_waitcnt lgkmcnt(1)
	v_cmp_ne_u32_e32 vcc, 0, v2
	s_cbranch_vccnz .LBB0_1503
	s_load_dwordx2 s[8:9], s[78:79], 0xc8
	s_load_dword s7, s[78:79], 0xd0
	s_add_u32 s4, s94, 0x28200
	s_addc_u32 s5, s95, 0
	s_add_u32 s6, s94, 0x28400
	s_waitcnt lgkmcnt(0)
	s_mul_i32 s33, s9, s8
	s_mul_i32 s33, s33, s7
	s_addc_u32 s7, s95, 0
	s_add_u32 s8, s94, 0x28500
	s_addc_u32 s9, s95, 0
	s_add_u32 s10, s94, 0x28600
	s_addc_u32 s11, s95, 0
	s_add_u32 s12, s94, 0x28700
	s_addc_u32 s13, s95, 0
	s_add_u32 s14, s94, 0x28800
	s_addc_u32 s15, s95, 0
	s_add_u32 s16, s94, 0x28900
	s_addc_u32 s17, s95, 0
	s_add_u32 s18, s94, 0x28a00
	s_addc_u32 s19, s95, 0
	s_add_u32 s20, s94, 0x28b00
	s_addc_u32 s21, s95, 0
	s_add_u32 s22, s94, 0x28c00
	s_addc_u32 s23, s95, 0
	s_add_u32 s24, s94, 0x28d00
	s_addc_u32 s25, s95, 0
	s_add_u32 s26, s94, 0x28e00
	s_addc_u32 s27, s95, 0
	s_add_u32 s28, s94, 0x28f00
	s_addc_u32 s29, s95, 0
	s_add_u32 s30, s94, 0x29000
	s_addc_u32 s31, s95, 0
	s_add_u32 s34, s94, 0x29100
	s_addc_u32 s35, s95, 0
	s_add_u32 s36, s94, 0x29200
	s_addc_u32 s37, s95, 0
	s_add_u32 s38, s94, 0x29300
	s_addc_u32 s39, s95, 0
	s_mov_b32 s46, 1
	v_mov_b32_e32 v16, 0
	s_branch .LBB0_1491
